# Mamba conv: the 8 token rows of a thread's block requested together (register prefetch) instead of one load per vmcnt(0)
# speedup vs baseline: 1.0077x; 1.0002x over previous
.LBB0_2320:
	s_or_b64 exec, exec, s[0:1]
	v_mad_i64_i32 v[110:111], s[0:1], v31, s14, 0
	v_lshl_add_u64 v[32:33], v[110:111], 1, v[68:69]
	global_load_dwordx4 v[118:121], v[32:33], off
	s_mov_b64 s[98:99], 0x1800
	v_lshl_add_u64 v[132:133], v[32:33], 0, s[98:99]
	global_load_dwordx4 v[132:135], v[132:133], off
	s_mov_b64 s[98:99], 0x3000
	v_lshl_add_u64 v[136:137], v[32:33], 0, s[98:99]
	global_load_dwordx4 v[136:139], v[136:137], off
	s_mov_b64 s[98:99], 0x4800
	v_lshl_add_u64 v[140:141], v[32:33], 0, s[98:99]
	global_load_dwordx4 v[140:143], v[140:141], off
	s_mov_b64 s[98:99], 0x6000
	v_lshl_add_u64 v[144:145], v[32:33], 0, s[98:99]
	global_load_dwordx4 v[144:147], v[144:145], off
	s_mov_b64 s[98:99], 0x7800
	v_lshl_add_u64 v[148:149], v[32:33], 0, s[98:99]
	global_load_dwordx4 v[148:151], v[148:149], off
	s_mov_b64 s[98:99], 0x9000
	v_lshl_add_u64 v[152:153], v[32:33], 0, s[98:99]
	global_load_dwordx4 v[152:155], v[152:153], off
	s_mov_b64 s[98:99], 0xa800
	v_lshl_add_u64 v[156:157], v[32:33], 0, s[98:99]
	global_load_dwordx4 v[156:159], v[156:157], off
	v_cmp_gt_i32_e64 s[0:1], 16, v30
	v_cmp_lt_i32_e32 vcc, 15, v30
	s_waitcnt vmcnt(7)
	v_lshlrev_b32_e32 v117, 16, v118
	v_cndmask_b32_e64 v95, 5, v130, s[0:1]
	v_mad_i64_i32 v[98:99], s[0:1], v30, 3, 0
	v_and_b32_e32 v43, 0xffff0000, v118
	v_lshlrev_b32_e32 v113, 16, v119
	v_and_b32_e32 v45, 0xffff0000, v119
	v_lshlrev_b32_e32 v105, 16, v120
	v_and_b32_e32 v31, 0xffff0000, v120
	v_lshlrev_b32_e32 v101, 16, v121
	v_and_b32_e32 v33, 0xffff0000, v121
	v_cmp_ge_i32_e64 s[0:1], v90, v95
	s_and_saveexec_b64 s[10:11], s[0:1]
	s_cbranch_execz .LBB0_2326
	s_and_saveexec_b64 s[0:1], vcc
	s_xor_b64 s[0:1], exec, s[0:1]
	v_add_u32_e32 v88, -5, v90
	v_lshl_add_u64 v[118:119], v[92:93], 0, v[88:89]
	s_or_saveexec_b64 s[0:1], s[0:1]
	v_mov_b64_e32 v[120:121], 0x182d0000
	s_xor_b64 exec, exec, s[0:1]
	v_add_u32_e32 v118, 0xfffff803, v90
	v_ashrrev_i32_e32 v119, 31, v118
	v_lshl_add_u64 v[118:119], v[98:99], 0, v[118:119]
	v_mov_b64_e32 v[120:121], 0x10240000
	s_or_b64 exec, exec, s[0:1]
	v_readlane_b32 s16, v252, 12
	v_readlane_b32 s22, v252, 18
	v_readlane_b32 s23, v252, 19
	v_mov_b32_e32 v42, v117
	v_mov_b32_e32 v44, v113
	v_lshl_add_u64 v[120:121], s[22:23], 0, v[120:121]
	v_mad_u64_u32 v[120:121], s[0:1], v118, s5, v[120:121]
	v_mov_b32_e32 v30, v121
	v_mad_u64_u32 v[118:119], s[0:1], v119, s5, v[30:31]
	v_mov_b32_e32 v121, v118
	v_lshl_add_u64 v[118:119], v[64:65], 2, v[120:121]
	v_mov_b32_e32 v30, v105
	v_mov_b32_e32 v32, v101
	v_readlane_b32 s17, v252, 13
	v_readlane_b32 s18, v252, 14
	v_readlane_b32 s19, v252, 15
	v_readlane_b32 s20, v252, 16
	v_readlane_b32 s21, v252, 17
	global_store_dwordx4 v[118:119], v[42:45], off
	global_store_dwordx4 v[118:119], v[30:33], off offset:16
.LBB0_2326:
	s_or_b64 exec, exec, s[10:11]
	v_mov_b32_e32 v47, v38
	v_pk_mul_f32 v[46:47], v[86:87], v[46:47]
	v_pk_mul_f32 v[118:119], v[18:19], v[114:115]
	v_add_f32_e32 v27, v2, v46
	v_add_f32_e32 v27, v27, v47
	v_pk_mul_f32 v[46:47], v[84:85], v[116:117]
	v_add_f32_e32 v29, v3, v118
	v_add_f32_e32 v27, v27, v46
	v_add_f32_e32 v27, v27, v47
	v_mul_f32_e32 v30, 0xbfb8aa3b, v27
	v_exp_f32_e32 v30, v30
	v_mov_b32_e32 v42, v55
	v_add_f32_e32 v29, v29, v119
	v_pk_mul_f32 v[118:119], v[10:11], v[42:43]
	v_add_f32_e32 v30, 1.0, v30
	v_rcp_f32_e32 v30, v30
	v_add_f32_e32 v29, v29, v118
	v_add_f32_e32 v29, v29, v119
	v_mov_b32_e32 v49, v40
	v_mul_f32_e32 v27, v27, v30
	v_mul_f32_e32 v30, 0xbfb8aa3b, v29
	v_exp_f32_e32 v30, v30
	v_pk_mul_f32 v[48:49], v[82:83], v[48:49]
	v_pk_mul_f32 v[118:119], v[20:21], v[108:109]
	v_mov_b32_e32 v44, v57
	v_add_f32_e32 v30, 1.0, v30
	v_rcp_f32_e32 v30, v30
	v_mov_b32_e32 v35, v26
	v_pk_mul_f32 v[34:35], v[78:79], v[34:35]
	v_mov_b32_e32 v37, v28
	v_mul_f32_e32 v29, v29, v30
	v_cvt_pk_bf16_f32 v46, v27, v29
	v_add_f32_e32 v27, v4, v48
	v_add_f32_e32 v27, v27, v49
	v_pk_mul_f32 v[48:49], v[80:81], v[112:113]
	v_add_f32_e32 v29, v5, v118
	v_add_f32_e32 v27, v27, v48
	v_add_f32_e32 v27, v27, v49
	v_mul_f32_e32 v30, 0xbfb8aa3b, v27
	v_exp_f32_e32 v30, v30
	v_add_f32_e32 v29, v29, v119
	v_pk_mul_f32 v[118:119], v[12:13], v[44:45]
	v_pk_mul_f32 v[48:49], v[22:23], v[106:107]
	v_add_f32_e32 v30, 1.0, v30
	v_rcp_f32_e32 v30, v30
	v_add_f32_e32 v29, v29, v118
	v_add_f32_e32 v29, v29, v119
	v_mul_f32_e32 v27, v27, v30
	v_mul_f32_e32 v30, 0xbfb8aa3b, v29
	v_exp_f32_e32 v30, v30
	s_nop 0
	v_add_f32_e32 v30, 1.0, v30
	v_rcp_f32_e32 v30, v30
	s_nop 0
	v_mul_f32_e32 v29, v29, v30
	v_cvt_pk_bf16_f32 v47, v27, v29
	v_add_f32_e32 v27, v6, v34
	v_add_f32_e32 v27, v27, v35
	v_pk_mul_f32 v[34:35], v[76:77], v[104:105]
	v_add_f32_e32 v29, v7, v48
	v_add_f32_e32 v27, v27, v34
	v_add_f32_e32 v27, v27, v35
	v_mul_f32_e32 v32, 0xbfb8aa3b, v27
	v_exp_f32_e32 v32, v32
	v_mov_b32_e32 v30, v51
	v_add_f32_e32 v29, v29, v49
	v_pk_mul_f32 v[48:49], v[14:15], v[30:31]
	v_add_f32_e32 v32, 1.0, v32
	v_rcp_f32_e32 v32, v32
	v_add_f32_e32 v29, v29, v48
	v_add_f32_e32 v29, v29, v49
	v_pk_mul_f32 v[34:35], v[74:75], v[36:37]
	v_mul_f32_e32 v27, v27, v32
	v_mul_f32_e32 v32, 0xbfb8aa3b, v29
	v_exp_f32_e32 v32, v32
	v_pk_mul_f32 v[36:37], v[24:25], v[102:103]
	v_add_f32_e32 v32, 1.0, v32
	v_rcp_f32_e32 v32, v32
	s_nop 0
	v_mul_f32_e32 v29, v29, v32
	v_cvt_pk_bf16_f32 v48, v27, v29
	v_add_f32_e32 v27, v8, v34
	v_add_f32_e32 v27, v27, v35
	v_pk_mul_f32 v[34:35], v[72:73], v[100:101]
	v_add_f32_e32 v29, v9, v36
	v_add_f32_e32 v27, v27, v34
	v_add_f32_e32 v27, v27, v35
	v_mul_f32_e32 v34, 0xbfb8aa3b, v27
	v_exp_f32_e32 v34, v34
	v_mov_b32_e32 v32, v53
	v_add_f32_e32 v29, v29, v37
	v_pk_mul_f32 v[36:37], v[16:17], v[32:33]
	v_add_f32_e32 v34, 1.0, v34
	v_rcp_f32_e32 v34, v34
	v_add_f32_e32 v29, v29, v36
	v_add_f32_e32 v29, v29, v37
	v_mul_f32_e32 v27, v27, v34
	v_mul_f32_e32 v34, 0xbfb8aa3b, v29
	v_exp_f32_e32 v34, v34
	s_nop 0
	v_add_f32_e32 v34, 1.0, v34
	v_rcp_f32_e32 v34, v34
	s_nop 0
	v_mul_f32_e32 v29, v29, v34
	v_cvt_pk_bf16_f32 v49, v27, v29
	v_add_u32_e32 v27, 4, v63
	v_lshl_add_u64 v[34:35], v[110:111], 1, v[70:71]
	v_mad_i64_i32 v[124:125], s[0:1], v27, s14, 0
	global_store_dwordx4 v[34:35], v[46:49], off
	v_lshl_add_u64 v[34:35], v[124:125], 1, v[68:69]
	v_cmp_ge_i32_e64 s[0:1], v96, v95
	s_waitcnt vmcnt(7)
	v_mov_b32_e32 v34, v132
	v_mov_b32_e32 v35, v133
	v_mov_b32_e32 v36, v134
	v_mov_b32_e32 v37, v135
	v_lshlrev_b32_e32 v123, 16, v34
	v_and_b32_e32 v47, 0xffff0000, v34
	v_lshlrev_b32_e32 v121, 16, v35
	v_and_b32_e32 v49, 0xffff0000, v35
	v_lshlrev_b32_e32 v119, 16, v36
	v_and_b32_e32 v35, 0xffff0000, v36
	v_lshlrev_b32_e32 v111, 16, v37
	v_and_b32_e32 v37, 0xffff0000, v37
	s_and_saveexec_b64 s[10:11], s[0:1]
	s_cbranch_execz .LBB0_2332
	s_and_saveexec_b64 s[0:1], vcc
	s_xor_b64 s[0:1], exec, s[0:1]
	v_add_u32_e32 v88, -4, v90
	v_lshl_add_u64 v[126:127], v[92:93], 0, v[88:89]
	s_or_saveexec_b64 s[0:1], s[0:1]
	v_mov_b64_e32 v[128:129], 0x182d0000
	s_xor_b64 exec, exec, s[0:1]
	v_add_u32_e32 v126, 0xfffff804, v90
	v_ashrrev_i32_e32 v127, 31, v126
	v_lshl_add_u64 v[126:127], v[98:99], 0, v[126:127]
	v_mov_b64_e32 v[128:129], 0x10240000
	s_or_b64 exec, exec, s[0:1]
	v_readlane_b32 s16, v252, 12
	v_readlane_b32 s22, v252, 18
	v_readlane_b32 s23, v252, 19
	v_mov_b32_e32 v46, v123
	v_mov_b32_e32 v48, v121
	v_lshl_add_u64 v[128:129], s[22:23], 0, v[128:129]
	v_mad_u64_u32 v[128:129], s[0:1], v126, s5, v[128:129]
	v_mov_b32_e32 v34, v129
	v_mad_u64_u32 v[126:127], s[0:1], v127, s5, v[34:35]
	v_mov_b32_e32 v129, v126
	v_lshl_add_u64 v[126:127], v[64:65], 2, v[128:129]
	v_mov_b32_e32 v34, v119
	v_mov_b32_e32 v36, v111
	v_readlane_b32 s17, v252, 13
	v_readlane_b32 s18, v252, 14
	v_readlane_b32 s19, v252, 15
	v_readlane_b32 s20, v252, 16
	v_readlane_b32 s21, v252, 17
	global_store_dwordx4 v[126:127], v[46:49], off
	global_store_dwordx4 v[126:127], v[34:37], off offset:16
.LBB0_2332:
	s_or_b64 exec, exec, s[10:11]
	v_mov_b32_e32 v39, v116
	v_pk_mul_f32 v[38:39], v[86:87], v[38:39]
	v_mov_b32_e32 v122, v117
	v_add_f32_e32 v27, v2, v38
	v_add_f32_e32 v27, v27, v39
	v_pk_mul_f32 v[38:39], v[84:85], v[122:123]
	v_mov_b32_e32 v54, v115
	v_add_f32_e32 v27, v27, v38
	v_add_f32_e32 v27, v27, v39
	v_pk_mul_f32 v[54:55], v[18:19], v[54:55]
	v_mul_f32_e32 v34, 0xbfb8aa3b, v27
	v_add_f32_e32 v29, v3, v54
	v_mov_b32_e32 v46, v43
	v_exp_f32_e32 v34, v34
	v_add_f32_e32 v29, v29, v55
	v_pk_mul_f32 v[38:39], v[10:11], v[46:47]
	v_mov_b32_e32 v41, v112
	v_add_f32_e32 v29, v29, v38
	v_add_f32_e32 v29, v29, v39
	v_add_f32_e32 v34, 1.0, v34
	v_mul_f32_e32 v36, 0xbfb8aa3b, v29
	v_rcp_f32_e32 v34, v34
	v_exp_f32_e32 v36, v36
	v_mov_b32_e32 v56, v109
	v_pk_mul_f32 v[38:39], v[82:83], v[40:41]
	v_pk_mul_f32 v[40:41], v[20:21], v[56:57]
	v_mul_f32_e32 v27, v27, v34
	v_add_f32_e32 v34, 1.0, v36
	v_add_f32_e32 v36, v4, v38
	v_add_f32_e32 v38, v5, v40
	v_mov_b32_e32 v120, v113
	v_add_f32_e32 v36, v36, v39
	v_add_f32_e32 v40, v38, v41
	v_pk_mul_f32 v[38:39], v[80:81], v[120:121]
	v_mov_b32_e32 v48, v45
	v_add_f32_e32 v36, v36, v38
	v_add_f32_e32 v36, v36, v39
	v_mul_f32_e32 v38, 0xbfb8aa3b, v36
	v_exp_f32_e32 v41, v38
	v_pk_mul_f32 v[38:39], v[12:13], v[48:49]
	v_rcp_f32_e32 v34, v34
	v_add_f32_e32 v38, v40, v38
	v_add_f32_e32 v39, v38, v39
	v_add_f32_e32 v38, 1.0, v41
	v_rcp_f32_e32 v40, v38
	v_mul_f32_e32 v38, 0xbfb8aa3b, v39
	v_exp_f32_e32 v41, v38
	v_mul_f32_e32 v29, v29, v34
	v_cvt_pk_bf16_f32 v38, v27, v29
	v_mul_f32_e32 v29, v36, v40
	v_add_f32_e32 v27, 1.0, v41
	v_rcp_f32_e32 v36, v27
	v_mov_b32_e32 v27, v104
	v_pk_mul_f32 v[26:27], v[78:79], v[26:27]
	v_mov_b32_e32 v50, v107
	v_add_f32_e32 v26, v6, v26
	v_pk_mul_f32 v[40:41], v[22:23], v[50:51]
	v_mov_b32_e32 v118, v105
	v_add_f32_e32 v34, v7, v40
	v_add_f32_e32 v40, v26, v27
	v_pk_mul_f32 v[26:27], v[76:77], v[118:119]
	v_add_f32_e32 v41, v34, v41
	v_add_f32_e32 v26, v40, v26
	v_add_f32_e32 v40, v26, v27
	v_mul_f32_e32 v26, 0xbfb8aa3b, v40
	v_mov_b32_e32 v34, v31
	v_exp_f32_e32 v50, v26
	v_pk_mul_f32 v[26:27], v[14:15], v[34:35]
	v_mul_f32_e32 v36, v39, v36
	v_add_f32_e32 v26, v41, v26
	v_add_f32_e32 v41, v26, v27
	v_add_f32_e32 v26, 1.0, v50
	v_mul_f32_e32 v27, 0xbfb8aa3b, v41
	v_rcp_f32_e32 v26, v26
	v_exp_f32_e32 v27, v27
	v_cvt_pk_bf16_f32 v39, v29, v36
	v_mov_b32_e32 v29, v100
	v_mul_f32_e32 v40, v40, v26
	v_add_f32_e32 v50, 1.0, v27
	v_pk_mul_f32 v[26:27], v[74:75], v[28:29]
	v_mov_b32_e32 v52, v103
	v_add_f32_e32 v26, v8, v26
	v_mov_b32_e32 v110, v101
	v_pk_mul_f32 v[28:29], v[24:25], v[52:53]
	v_add_f32_e32 v36, v26, v27
	v_pk_mul_f32 v[26:27], v[72:73], v[110:111]
	v_add_f32_e32 v28, v9, v28
	v_add_f32_e32 v26, v36, v26
	v_mov_b32_e32 v36, v33
	v_add_f32_e32 v51, v28, v29
	v_pk_mul_f32 v[28:29], v[16:17], v[36:37]
	v_add_f32_e32 v26, v26, v27
	v_add_f32_e32 v28, v51, v28
	v_add_f32_e32 v27, v28, v29
	v_mul_f32_e32 v28, 0xbfb8aa3b, v26
	v_mul_f32_e32 v29, 0xbfb8aa3b, v27
	v_exp_f32_e32 v28, v28
	v_exp_f32_e32 v29, v29
	v_rcp_f32_e32 v50, v50
	v_add_f32_e32 v28, 1.0, v28
	v_add_f32_e32 v29, 1.0, v29
	v_rcp_f32_e32 v28, v28
	v_rcp_f32_e32 v29, v29
	v_mul_f32_e32 v41, v41, v50
	v_cvt_pk_bf16_f32 v40, v40, v41
	v_mul_f32_e32 v26, v26, v28
	v_mul_f32_e32 v27, v27, v29
	v_cvt_pk_bf16_f32 v41, v26, v27
	v_lshl_add_u64 v[26:27], v[124:125], 1, v[70:71]
	global_store_dwordx4 v[26:27], v[38:41], off
	v_add_u32_e32 v26, 5, v63
	v_mad_i64_i32 v[54:55], s[0:1], v26, s14, 0
	v_lshl_add_u64 v[26:27], v[54:55], 1, v[68:69]
	v_cmp_ge_i32_e64 s[0:1], v94, v95
	s_waitcnt vmcnt(7)
	v_mov_b32_e32 v26, v136
	v_mov_b32_e32 v27, v137
	v_mov_b32_e32 v28, v138
	v_mov_b32_e32 v29, v139
	v_lshlrev_b32_e32 v107, 16, v26
	v_and_b32_e32 v39, 0xffff0000, v26
	v_lshlrev_b32_e32 v57, 16, v27
	v_and_b32_e32 v41, 0xffff0000, v27
	v_lshlrev_b32_e32 v53, 16, v28
	v_and_b32_e32 v27, 0xffff0000, v28
	v_lshlrev_b32_e32 v51, 16, v29
	v_and_b32_e32 v29, 0xffff0000, v29
	s_and_saveexec_b64 s[10:11], s[0:1]
	s_cbranch_execz .LBB0_2338
	s_and_saveexec_b64 s[0:1], vcc
	s_xor_b64 s[0:1], exec, s[0:1]
	v_add_u32_e32 v88, -3, v90
	v_lshl_add_u64 v[102:103], v[92:93], 0, v[88:89]
	s_or_saveexec_b64 s[0:1], s[0:1]
	v_mov_b64_e32 v[108:109], 0x182d0000
	s_xor_b64 exec, exec, s[0:1]
	v_add_u32_e32 v102, 0xfffff805, v90
	v_ashrrev_i32_e32 v103, 31, v102
	v_lshl_add_u64 v[102:103], v[98:99], 0, v[102:103]
	v_mov_b64_e32 v[108:109], 0x10240000
	s_or_b64 exec, exec, s[0:1]
	v_readlane_b32 s16, v252, 12
	v_readlane_b32 s22, v252, 18
	v_readlane_b32 s23, v252, 19
	v_mov_b32_e32 v38, v107
	v_mov_b32_e32 v40, v57
	v_lshl_add_u64 v[108:109], s[22:23], 0, v[108:109]
	v_mad_u64_u32 v[108:109], s[0:1], v102, s5, v[108:109]
	v_mov_b32_e32 v26, v109
	v_mad_u64_u32 v[102:103], s[0:1], v103, s5, v[26:27]
	v_mov_b32_e32 v109, v102
	v_lshl_add_u64 v[102:103], v[64:65], 2, v[108:109]
	v_mov_b32_e32 v26, v53
	v_mov_b32_e32 v28, v51
	v_readlane_b32 s17, v252, 13
	v_readlane_b32 s18, v252, 14
	v_readlane_b32 s19, v252, 15
	v_readlane_b32 s20, v252, 16
	v_readlane_b32 s21, v252, 17
	global_store_dwordx4 v[102:103], v[38:41], off
	global_store_dwordx4 v[102:103], v[26:29], off offset:16
.LBB0_2338:
	s_or_b64 exec, exec, s[10:11]
	v_pk_mul_f32 v[102:103], v[86:87], v[116:117]
	v_pk_mul_f32 v[42:43], v[18:19], v[42:43]
	v_add_f32_e32 v26, v2, v102
	v_add_f32_e32 v28, v3, v42
	v_mov_b32_e32 v106, v123
	v_add_f32_e32 v26, v26, v103
	v_add_f32_e32 v28, v28, v43
	v_pk_mul_f32 v[42:43], v[84:85], v[106:107]
	v_mov_b32_e32 v38, v47
	v_add_f32_e32 v26, v26, v42
	v_add_f32_e32 v26, v26, v43
	v_mul_f32_e32 v40, 0xbfb8aa3b, v26
	v_exp_f32_e32 v40, v40
	v_pk_mul_f32 v[102:103], v[10:11], v[38:39]
	v_pk_mul_f32 v[44:45], v[20:21], v[44:45]
	v_add_f32_e32 v28, v28, v102
	v_add_f32_e32 v40, 1.0, v40
	v_rcp_f32_e32 v40, v40
	v_add_f32_e32 v28, v28, v103
	v_pk_mul_f32 v[102:103], v[82:83], v[112:113]
	v_mov_b32_e32 v56, v121
	v_mul_f32_e32 v26, v26, v40
	v_mul_f32_e32 v40, 0xbfb8aa3b, v28
	v_exp_f32_e32 v40, v40
	v_pk_mul_f32 v[30:31], v[22:23], v[30:31]
	v_mov_b32_e32 v52, v119
	v_pk_mul_f32 v[32:33], v[24:25], v[32:33]
	v_add_f32_e32 v40, 1.0, v40
	v_rcp_f32_e32 v40, v40
	v_mov_b32_e32 v50, v111
	v_mul_f32_e32 v28, v28, v40
	v_cvt_pk_bf16_f32 v42, v26, v28
	v_add_f32_e32 v26, v4, v102
	v_add_f32_e32 v28, v5, v44
	v_add_f32_e32 v26, v26, v103
	v_add_f32_e32 v28, v28, v45
	v_pk_mul_f32 v[44:45], v[80:81], v[56:57]
	v_mov_b32_e32 v40, v49
	v_add_f32_e32 v26, v26, v44
	v_add_f32_e32 v26, v26, v45
	v_mul_f32_e32 v43, 0xbfb8aa3b, v26
	v_exp_f32_e32 v43, v43
	v_pk_mul_f32 v[102:103], v[12:13], v[40:41]
	v_pk_mul_f32 v[44:45], v[78:79], v[104:105]
	v_add_f32_e32 v28, v28, v102
	v_add_f32_e32 v43, 1.0, v43
	v_rcp_f32_e32 v43, v43
	v_add_f32_e32 v28, v28, v103
	v_mul_f32_e32 v26, v26, v43
	v_mul_f32_e32 v43, 0xbfb8aa3b, v28
	v_exp_f32_e32 v43, v43
	s_nop 0
	v_add_f32_e32 v43, 1.0, v43
	v_rcp_f32_e32 v43, v43
	s_nop 0
	v_mul_f32_e32 v28, v28, v43
	v_cvt_pk_bf16_f32 v43, v26, v28
	v_add_f32_e32 v26, v6, v44
	v_add_f32_e32 v28, v7, v30
	v_add_f32_e32 v26, v26, v45
	v_add_f32_e32 v28, v28, v31
	v_pk_mul_f32 v[30:31], v[76:77], v[52:53]
	s_nop 0
	v_add_f32_e32 v30, v26, v30
	v_add_f32_e32 v30, v30, v31
	v_mul_f32_e32 v31, 0xbfb8aa3b, v30
	v_exp_f32_e32 v31, v31
	v_mov_b32_e32 v26, v35
	v_pk_mul_f32 v[44:45], v[14:15], v[26:27]
	v_add_f32_e32 v31, 1.0, v31
	v_rcp_f32_e32 v31, v31
	v_add_f32_e32 v28, v28, v44
	v_add_f32_e32 v28, v28, v45
	v_mul_f32_e32 v30, v30, v31
	v_mul_f32_e32 v31, 0xbfb8aa3b, v28
	v_exp_f32_e32 v31, v31
	s_nop 0
	v_add_f32_e32 v31, 1.0, v31
	v_rcp_f32_e32 v31, v31
	s_nop 0
	v_mul_f32_e32 v28, v28, v31
	v_cvt_pk_bf16_f32 v44, v30, v28
	v_pk_mul_f32 v[30:31], v[74:75], v[100:101]
	s_nop 0
	v_add_f32_e32 v28, v8, v30
	v_add_f32_e32 v30, v9, v32
	v_add_f32_e32 v28, v28, v31
	v_add_f32_e32 v45, v30, v33
	v_pk_mul_f32 v[30:31], v[72:73], v[50:51]
	s_nop 0
	v_add_f32_e32 v30, v28, v30
	v_mov_b32_e32 v28, v37
	v_pk_mul_f32 v[32:33], v[16:17], v[28:29]
	v_add_f32_e32 v30, v30, v31
	v_add_f32_e32 v32, v45, v32
	v_add_f32_e32 v31, v32, v33
	v_mul_f32_e32 v32, 0xbfb8aa3b, v30
	v_exp_f32_e32 v32, v32
	s_nop 0
	v_add_f32_e32 v32, 1.0, v32
	v_rcp_f32_e32 v32, v32
	s_nop 0
	v_mul_f32_e32 v30, v30, v32
	v_mul_f32_e32 v32, 0xbfb8aa3b, v31
	v_exp_f32_e32 v32, v32
	s_nop 0
	v_add_f32_e32 v32, 1.0, v32
	v_rcp_f32_e32 v32, v32
	s_nop 0
	v_mul_f32_e32 v31, v31, v32
	v_cvt_pk_bf16_f32 v45, v30, v31
	v_lshl_add_u64 v[30:31], v[54:55], 1, v[70:71]
	global_store_dwordx4 v[30:31], v[42:45], off
	v_add_u32_e32 v30, 6, v63
	v_mad_i64_i32 v[108:109], s[0:1], v30, s14, 0
	v_lshl_add_u64 v[30:31], v[108:109], 1, v[68:69]
	s_waitcnt vmcnt(7)
	v_mov_b32_e32 v30, v140
	v_mov_b32_e32 v31, v141
	v_mov_b32_e32 v32, v142
	v_mov_b32_e32 v33, v143
	v_lshlrev_b32_e32 v105, 16, v30
	v_and_b32_e32 v43, 0xffff0000, v30
	v_or_b32_e32 v30, 3, v90
	v_lshlrev_b32_e32 v103, 16, v31
	v_and_b32_e32 v45, 0xffff0000, v31
	v_lshlrev_b32_e32 v101, 16, v32
	v_and_b32_e32 v31, 0xffff0000, v32
	v_lshlrev_b32_e32 v55, 16, v33
	v_and_b32_e32 v33, 0xffff0000, v33
	v_cmp_ge_i32_e64 s[0:1], v30, v95
	s_and_saveexec_b64 s[10:11], s[0:1]
	s_cbranch_execz .LBB0_2344
	s_and_saveexec_b64 s[0:1], vcc
	s_xor_b64 s[0:1], exec, s[0:1]
	v_add_u32_e32 v88, -2, v90
	v_lshl_add_u64 v[112:113], v[92:93], 0, v[88:89]
	s_or_saveexec_b64 s[0:1], s[0:1]
	v_mov_b64_e32 v[114:115], 0x182d0000
	s_xor_b64 exec, exec, s[0:1]
	v_add_u32_e32 v112, 0xfffff806, v90
	v_ashrrev_i32_e32 v113, 31, v112
	v_lshl_add_u64 v[112:113], v[98:99], 0, v[112:113]
	v_mov_b64_e32 v[114:115], 0x10240000
	s_or_b64 exec, exec, s[0:1]
	v_readlane_b32 s16, v252, 12
	v_readlane_b32 s22, v252, 18
	v_readlane_b32 s23, v252, 19
	v_mov_b32_e32 v42, v105
	v_mov_b32_e32 v44, v103
	v_lshl_add_u64 v[114:115], s[22:23], 0, v[114:115]
	v_mad_u64_u32 v[114:115], s[0:1], v112, s5, v[114:115]
	v_mov_b32_e32 v30, v115
	v_mad_u64_u32 v[112:113], s[0:1], v113, s5, v[30:31]
	v_mov_b32_e32 v115, v112
	v_lshl_add_u64 v[112:113], v[64:65], 2, v[114:115]
	v_mov_b32_e32 v30, v101
	v_mov_b32_e32 v32, v55
	v_readlane_b32 s17, v252, 13
	v_readlane_b32 s18, v252, 14
	v_readlane_b32 s19, v252, 15
	v_readlane_b32 s20, v252, 16
	v_readlane_b32 s21, v252, 17
	global_store_dwordx4 v[112:113], v[42:45], off
	global_store_dwordx4 v[112:113], v[30:33], off offset:16
.LBB0_2344:
	s_or_b64 exec, exec, s[10:11]
	v_pk_mul_f32 v[112:113], v[86:87], v[122:123]
	v_pk_mul_f32 v[46:47], v[18:19], v[46:47]
	v_add_f32_e32 v30, v2, v112
	v_add_f32_e32 v32, v3, v46
	v_mov_b32_e32 v104, v107
	v_add_f32_e32 v30, v30, v113
	v_add_f32_e32 v32, v32, v47
	v_pk_mul_f32 v[46:47], v[84:85], v[104:105]
	v_mov_b32_e32 v42, v39
	v_add_f32_e32 v30, v30, v46
	v_add_f32_e32 v30, v30, v47
	v_mul_f32_e32 v44, 0xbfb8aa3b, v30
	v_exp_f32_e32 v44, v44
	v_pk_mul_f32 v[112:113], v[10:11], v[42:43]
	v_pk_mul_f32 v[48:49], v[20:21], v[48:49]
	v_add_f32_e32 v32, v32, v112
	v_add_f32_e32 v44, 1.0, v44
	v_rcp_f32_e32 v44, v44
	v_add_f32_e32 v32, v32, v113
	v_pk_mul_f32 v[112:113], v[82:83], v[120:121]
	v_mov_b32_e32 v102, v57
	v_mul_f32_e32 v30, v30, v44
	v_mul_f32_e32 v44, 0xbfb8aa3b, v32
	v_exp_f32_e32 v44, v44
	v_pk_mul_f32 v[34:35], v[22:23], v[34:35]
	v_mov_b32_e32 v100, v53
	v_pk_mul_f32 v[36:37], v[24:25], v[36:37]
	v_add_f32_e32 v44, 1.0, v44
	v_rcp_f32_e32 v44, v44
	v_mov_b32_e32 v54, v51
	v_mul_f32_e32 v32, v32, v44
	v_cvt_pk_bf16_f32 v46, v30, v32
	v_add_f32_e32 v30, v4, v112
	v_add_f32_e32 v32, v5, v48
	v_add_f32_e32 v30, v30, v113
	v_add_f32_e32 v32, v32, v49
	v_pk_mul_f32 v[48:49], v[80:81], v[102:103]
	v_mov_b32_e32 v44, v41
	v_add_f32_e32 v30, v30, v48
	v_add_f32_e32 v30, v30, v49
	v_mul_f32_e32 v47, 0xbfb8aa3b, v30
	v_exp_f32_e32 v47, v47
	v_pk_mul_f32 v[112:113], v[12:13], v[44:45]
	v_pk_mul_f32 v[48:49], v[78:79], v[118:119]
	v_add_f32_e32 v32, v32, v112
	v_add_f32_e32 v47, 1.0, v47
	v_rcp_f32_e32 v47, v47
	v_add_f32_e32 v32, v32, v113
	v_mul_f32_e32 v30, v30, v47
	v_mul_f32_e32 v47, 0xbfb8aa3b, v32
	v_exp_f32_e32 v47, v47
	s_nop 0
	v_add_f32_e32 v47, 1.0, v47
	v_rcp_f32_e32 v47, v47
	s_nop 0
	v_mul_f32_e32 v32, v32, v47
	v_cvt_pk_bf16_f32 v47, v30, v32
	v_add_f32_e32 v30, v6, v48
	v_add_f32_e32 v32, v7, v34
	v_add_f32_e32 v30, v30, v49
	v_add_f32_e32 v32, v32, v35
	v_pk_mul_f32 v[34:35], v[76:77], v[100:101]
	s_nop 0
	v_add_f32_e32 v34, v30, v34
	v_add_f32_e32 v34, v34, v35
	v_mul_f32_e32 v35, 0xbfb8aa3b, v34
	v_exp_f32_e32 v35, v35
	v_mov_b32_e32 v30, v27
	v_pk_mul_f32 v[48:49], v[14:15], v[30:31]
	v_add_f32_e32 v35, 1.0, v35
	v_rcp_f32_e32 v35, v35
	v_add_f32_e32 v32, v32, v48
	v_add_f32_e32 v32, v32, v49
	v_mul_f32_e32 v34, v34, v35
	v_mul_f32_e32 v35, 0xbfb8aa3b, v32
	v_exp_f32_e32 v35, v35
	s_nop 0
	v_add_f32_e32 v35, 1.0, v35
	v_rcp_f32_e32 v35, v35
	s_nop 0
	v_mul_f32_e32 v32, v32, v35
	v_cvt_pk_bf16_f32 v48, v34, v32
	v_pk_mul_f32 v[34:35], v[74:75], v[110:111]
	s_nop 0
	v_add_f32_e32 v32, v8, v34
	v_add_f32_e32 v34, v9, v36
	v_add_f32_e32 v32, v32, v35
	v_add_f32_e32 v49, v34, v37
	v_pk_mul_f32 v[34:35], v[72:73], v[54:55]
	s_nop 0
	v_add_f32_e32 v34, v32, v34
	v_mov_b32_e32 v32, v29
	v_pk_mul_f32 v[36:37], v[16:17], v[32:33]
	v_add_f32_e32 v34, v34, v35
	v_add_f32_e32 v36, v49, v36
	v_add_f32_e32 v35, v36, v37
	v_mul_f32_e32 v36, 0xbfb8aa3b, v34
	v_exp_f32_e32 v36, v36
	s_nop 0
	v_add_f32_e32 v36, 1.0, v36
	v_rcp_f32_e32 v36, v36
	s_nop 0
	v_mul_f32_e32 v34, v34, v36
	v_mul_f32_e32 v36, 0xbfb8aa3b, v35
	v_exp_f32_e32 v36, v36
	s_nop 0
	v_add_f32_e32 v36, 1.0, v36
	v_rcp_f32_e32 v36, v36
	s_nop 0
	v_mul_f32_e32 v35, v35, v36
	v_cvt_pk_bf16_f32 v49, v34, v35
	v_lshl_add_u64 v[34:35], v[108:109], 1, v[70:71]
	global_store_dwordx4 v[34:35], v[46:49], off
	v_add_u32_e32 v34, 7, v63
	v_mad_i64_i32 v[116:117], s[0:1], v34, s14, 0
	v_lshl_add_u64 v[34:35], v[116:117], 1, v[68:69]
	s_waitcnt vmcnt(7)
	v_mov_b32_e32 v34, v144
	v_mov_b32_e32 v35, v145
	v_mov_b32_e32 v36, v146
	v_mov_b32_e32 v37, v147
	v_lshlrev_b32_e32 v115, 16, v34
	v_and_b32_e32 v47, 0xffff0000, v34
	v_or_b32_e32 v34, 4, v90
	v_lshlrev_b32_e32 v113, 16, v35
	v_and_b32_e32 v49, 0xffff0000, v35
	v_lshlrev_b32_e32 v111, 16, v36
	v_and_b32_e32 v35, 0xffff0000, v36
	v_lshlrev_b32_e32 v109, 16, v37
	v_and_b32_e32 v37, 0xffff0000, v37
	v_cmp_ge_i32_e64 s[0:1], v34, v95
	s_and_saveexec_b64 s[10:11], s[0:1]
	s_cbranch_execz .LBB0_2350
	s_and_saveexec_b64 s[0:1], vcc
	s_xor_b64 s[0:1], exec, s[0:1]
	v_add_u32_e32 v88, -1, v90
	v_lshl_add_u64 v[118:119], v[92:93], 0, v[88:89]
	s_or_saveexec_b64 s[0:1], s[0:1]
	v_mov_b64_e32 v[120:121], 0x182d0000
	s_xor_b64 exec, exec, s[0:1]
	v_add_u32_e32 v118, 0xfffff807, v90
	v_ashrrev_i32_e32 v119, 31, v118
	v_lshl_add_u64 v[118:119], v[98:99], 0, v[118:119]
	v_mov_b64_e32 v[120:121], 0x10240000
	s_or_b64 exec, exec, s[0:1]
	v_readlane_b32 s16, v252, 12
	v_readlane_b32 s22, v252, 18
	v_readlane_b32 s23, v252, 19
	v_mov_b32_e32 v46, v115
	v_mov_b32_e32 v48, v113
	v_lshl_add_u64 v[120:121], s[22:23], 0, v[120:121]
	v_mad_u64_u32 v[120:121], s[0:1], v118, s5, v[120:121]
	v_mov_b32_e32 v34, v121
	v_mad_u64_u32 v[118:119], s[0:1], v119, s5, v[34:35]
	v_mov_b32_e32 v121, v118
	v_lshl_add_u64 v[118:119], v[64:65], 2, v[120:121]
	v_mov_b32_e32 v34, v111
	v_mov_b32_e32 v36, v109
	v_readlane_b32 s17, v252, 13
	v_readlane_b32 s18, v252, 14
	v_readlane_b32 s19, v252, 15
	v_readlane_b32 s20, v252, 16
	v_readlane_b32 s21, v252, 17
	global_store_dwordx4 v[118:119], v[46:49], off
	global_store_dwordx4 v[118:119], v[34:37], off offset:16
.LBB0_2350:
	s_or_b64 exec, exec, s[10:11]
	v_pk_mul_f32 v[106:107], v[86:87], v[106:107]
	v_pk_mul_f32 v[38:39], v[18:19], v[38:39]
	v_add_f32_e32 v34, v2, v106
	v_add_f32_e32 v36, v3, v38
	v_mov_b32_e32 v114, v105
	v_add_f32_e32 v34, v34, v107
	v_add_f32_e32 v36, v36, v39
	v_pk_mul_f32 v[38:39], v[84:85], v[114:115]
	v_mov_b32_e32 v46, v43
	v_add_f32_e32 v34, v34, v38
	v_add_f32_e32 v34, v34, v39
	v_mul_f32_e32 v38, 0xbfb8aa3b, v34
	v_exp_f32_e32 v38, v38
	v_pk_mul_f32 v[106:107], v[10:11], v[46:47]
	v_pk_mul_f32 v[56:57], v[82:83], v[56:57]
	v_add_f32_e32 v36, v36, v106
	v_add_f32_e32 v38, 1.0, v38
	v_rcp_f32_e32 v38, v38
	v_add_f32_e32 v36, v36, v107
	v_pk_mul_f32 v[40:41], v[20:21], v[40:41]
	v_mov_b32_e32 v112, v103
	v_mul_f32_e32 v34, v34, v38
	v_mul_f32_e32 v38, 0xbfb8aa3b, v36
	v_exp_f32_e32 v38, v38
	v_mov_b32_e32 v48, v45
	v_pk_mul_f32 v[26:27], v[22:23], v[26:27]
	v_mov_b32_e32 v110, v101
	v_add_f32_e32 v38, 1.0, v38
	v_rcp_f32_e32 v38, v38
	v_add_f32_e32 v26, v7, v26
	v_mov_b32_e32 v108, v55
	v_pk_mul_f32 v[28:29], v[24:25], v[28:29]
	v_mul_f32_e32 v36, v36, v38
	v_cvt_pk_bf16_f32 v38, v34, v36
	v_add_f32_e32 v34, v4, v56
	v_add_f32_e32 v36, v5, v40
	v_add_f32_e32 v34, v34, v57
	v_add_f32_e32 v36, v36, v41
	v_pk_mul_f32 v[40:41], v[80:81], v[112:113]
	v_pk_mul_f32 v[56:57], v[12:13], v[48:49]
	v_add_f32_e32 v34, v34, v40
	v_add_f32_e32 v34, v34, v41
	v_mul_f32_e32 v39, 0xbfb8aa3b, v34
	v_exp_f32_e32 v39, v39
	v_add_f32_e32 v36, v36, v56
	v_add_f32_e32 v36, v36, v57
	v_pk_mul_f32 v[40:41], v[78:79], v[52:53]
	v_add_f32_e32 v39, 1.0, v39
	v_rcp_f32_e32 v39, v39
	v_add_f32_e32 v28, v9, v28
	v_mul_f32_e32 v34, v34, v39
	v_mul_f32_e32 v39, 0xbfb8aa3b, v36
	v_exp_f32_e32 v39, v39
	s_nop 0
	v_add_f32_e32 v39, 1.0, v39
	v_rcp_f32_e32 v39, v39
	s_nop 0
	v_mul_f32_e32 v36, v36, v39
	v_cvt_pk_bf16_f32 v39, v34, v36
	v_add_f32_e32 v34, v6, v40
	v_add_f32_e32 v34, v34, v41
	v_add_f32_e32 v36, v26, v27
	v_pk_mul_f32 v[26:27], v[76:77], v[110:111]
	s_nop 0
	v_add_f32_e32 v26, v34, v26
	v_mov_b32_e32 v34, v31
	v_pk_mul_f32 v[40:41], v[14:15], v[34:35]
	v_add_f32_e32 v26, v26, v27
	v_add_f32_e32 v36, v36, v40
	v_add_f32_e32 v27, v36, v41
	v_mul_f32_e32 v36, 0xbfb8aa3b, v26
	v_exp_f32_e32 v36, v36
	v_add_f32_e32 v41, v28, v29
	v_add_f32_e32 v36, 1.0, v36
	v_rcp_f32_e32 v36, v36
	s_nop 0
	v_mul_f32_e32 v26, v26, v36
	v_mul_f32_e32 v36, 0xbfb8aa3b, v27
	v_exp_f32_e32 v36, v36
	s_nop 0
	v_add_f32_e32 v36, 1.0, v36
	v_rcp_f32_e32 v36, v36
	s_nop 0
	v_mul_f32_e32 v27, v27, v36
	v_cvt_pk_bf16_f32 v40, v26, v27
	v_pk_mul_f32 v[26:27], v[74:75], v[50:51]
	s_nop 0
	v_add_f32_e32 v26, v8, v26
	v_add_f32_e32 v36, v26, v27
	v_pk_mul_f32 v[26:27], v[72:73], v[108:109]
	s_nop 0
	v_add_f32_e32 v26, v36, v26
	v_mov_b32_e32 v36, v33
	v_pk_mul_f32 v[28:29], v[16:17], v[36:37]
	v_add_f32_e32 v26, v26, v27
	v_add_f32_e32 v28, v41, v28
	v_add_f32_e32 v27, v28, v29
	v_mul_f32_e32 v28, 0xbfb8aa3b, v26
	v_exp_f32_e32 v28, v28
	s_nop 0
	v_add_f32_e32 v28, 1.0, v28
	v_rcp_f32_e32 v28, v28
	s_nop 0
	v_mul_f32_e32 v26, v26, v28
	v_mul_f32_e32 v28, 0xbfb8aa3b, v27
	v_exp_f32_e32 v28, v28
	s_nop 0
	v_add_f32_e32 v28, 1.0, v28
	v_rcp_f32_e32 v28, v28
	s_nop 0
	v_mul_f32_e32 v27, v27, v28
	v_cvt_pk_bf16_f32 v41, v26, v27
	v_lshl_add_u64 v[26:27], v[116:117], 1, v[70:71]
	global_store_dwordx4 v[26:27], v[38:41], off
	v_add_u32_e32 v26, 8, v63
	v_mad_i64_i32 v[116:117], s[0:1], v26, s14, 0
	v_lshl_add_u64 v[26:27], v[116:117], 1, v[68:69]
	s_waitcnt vmcnt(7)
	v_mov_b32_e32 v26, v148
	v_mov_b32_e32 v27, v149
	v_mov_b32_e32 v28, v150
	v_mov_b32_e32 v29, v151
	v_lshlrev_b32_e32 v107, 16, v26
	v_and_b32_e32 v39, 0xffff0000, v26
	v_or_b32_e32 v26, 5, v90
	v_lshlrev_b32_e32 v57, 16, v27
	v_and_b32_e32 v41, 0xffff0000, v27
	v_lshlrev_b32_e32 v53, 16, v28
	v_and_b32_e32 v27, 0xffff0000, v28
	v_lshlrev_b32_e32 v51, 16, v29
	v_and_b32_e32 v29, 0xffff0000, v29
	v_cmp_ge_i32_e64 s[0:1], v26, v95
	s_and_saveexec_b64 s[10:11], s[0:1]
	s_cbranch_execz .LBB0_2356
	s_and_saveexec_b64 s[0:1], vcc
	s_xor_b64 s[0:1], exec, s[0:1]
	v_mov_b32_e32 v91, v89
	v_lshl_add_u64 v[118:119], v[92:93], 0, v[90:91]
	s_or_saveexec_b64 s[0:1], s[0:1]
	v_mov_b64_e32 v[120:121], 0x182d0000
	s_xor_b64 exec, exec, s[0:1]
	v_add_u32_e32 v118, 0xfffff808, v90
	v_ashrrev_i32_e32 v119, 31, v118
	v_lshl_add_u64 v[118:119], v[98:99], 0, v[118:119]
	v_mov_b64_e32 v[120:121], 0x10240000
	s_or_b64 exec, exec, s[0:1]
	v_readlane_b32 s16, v252, 12
	v_readlane_b32 s22, v252, 18
	v_readlane_b32 s23, v252, 19
	v_mov_b32_e32 v38, v107
	v_mov_b32_e32 v40, v57
	v_lshl_add_u64 v[120:121], s[22:23], 0, v[120:121]
	v_mad_u64_u32 v[120:121], s[0:1], v118, s5, v[120:121]
	v_mov_b32_e32 v26, v121
	v_mad_u64_u32 v[118:119], s[0:1], v119, s5, v[26:27]
	v_mov_b32_e32 v121, v118
	v_lshl_add_u64 v[118:119], v[64:65], 2, v[120:121]
	v_mov_b32_e32 v26, v53
	v_mov_b32_e32 v28, v51
	v_readlane_b32 s17, v252, 13
	v_readlane_b32 s18, v252, 14
	v_readlane_b32 s19, v252, 15
	v_readlane_b32 s20, v252, 16
	v_readlane_b32 s21, v252, 17
	global_store_dwordx4 v[118:119], v[38:41], off
	global_store_dwordx4 v[118:119], v[26:29], off offset:16
.LBB0_2356:
	s_or_b64 exec, exec, s[10:11]
	v_pk_mul_f32 v[104:105], v[86:87], v[104:105]
	v_pk_mul_f32 v[42:43], v[18:19], v[42:43]
	v_add_f32_e32 v26, v2, v104
	v_add_f32_e32 v28, v3, v42
	v_mov_b32_e32 v106, v115
	v_add_f32_e32 v26, v26, v105
	v_add_f32_e32 v28, v28, v43
	v_pk_mul_f32 v[42:43], v[84:85], v[106:107]
	v_mov_b32_e32 v38, v47
	v_add_f32_e32 v26, v26, v42
	v_add_f32_e32 v26, v26, v43
	v_mul_f32_e32 v40, 0xbfb8aa3b, v26
	v_exp_f32_e32 v40, v40
	v_pk_mul_f32 v[42:43], v[10:11], v[38:39]
	v_pk_mul_f32 v[44:45], v[20:21], v[44:45]
	v_add_f32_e32 v28, v28, v42
	v_add_f32_e32 v28, v28, v43
	v_add_f32_e32 v40, 1.0, v40
	v_mul_f32_e32 v42, 0xbfb8aa3b, v28
	v_rcp_f32_e32 v40, v40
	v_exp_f32_e32 v42, v42
	v_mov_b32_e32 v56, v113
	v_pk_mul_f32 v[30:31], v[22:23], v[30:31]
	v_mul_f32_e32 v26, v26, v40
	v_add_f32_e32 v40, 1.0, v42
	v_pk_mul_f32 v[42:43], v[82:83], v[102:103]
	v_rcp_f32_e32 v50, v40
	v_add_f32_e32 v40, v4, v42
	v_add_f32_e32 v42, v5, v44
	v_add_f32_e32 v40, v40, v43
	v_add_f32_e32 v44, v42, v45
	v_pk_mul_f32 v[42:43], v[80:81], v[56:57]
	v_mul_f32_e32 v28, v28, v50
	v_add_f32_e32 v42, v40, v42
	v_add_f32_e32 v45, v42, v43
	v_mul_f32_e32 v42, 0xbfb8aa3b, v45
	v_exp_f32_e32 v52, v42
	v_mov_b32_e32 v40, v49
	v_pk_mul_f32 v[42:43], v[12:13], v[40:41]
	v_add_f32_e32 v30, v7, v30
	v_add_f32_e32 v42, v44, v42
	v_add_f32_e32 v43, v42, v43
	v_add_f32_e32 v42, 1.0, v52
	v_rcp_f32_e32 v44, v42
	v_mul_f32_e32 v42, 0xbfb8aa3b, v43
	v_exp_f32_e32 v52, v42
	v_cvt_pk_bf16_f32 v42, v26, v28
	v_mul_f32_e32 v28, v45, v44
	v_pk_mul_f32 v[44:45], v[78:79], v[100:101]
	v_add_f32_e32 v26, 1.0, v52
	v_rcp_f32_e32 v50, v26
	v_add_f32_e32 v26, v6, v44
	v_mov_b32_e32 v52, v111
	v_add_f32_e32 v26, v26, v45
	v_add_f32_e32 v44, v30, v31
	v_pk_mul_f32 v[30:31], v[76:77], v[52:53]
	v_mul_f32_e32 v43, v43, v50
	v_add_f32_e32 v30, v26, v30
	v_add_f32_e32 v45, v30, v31
	v_mul_f32_e32 v30, 0xbfb8aa3b, v45
	v_mov_b32_e32 v26, v35
	v_exp_f32_e32 v88, v30
	v_pk_mul_f32 v[30:31], v[14:15], v[26:27]
	v_pk_mul_f32 v[32:33], v[24:25], v[32:33]
	v_add_f32_e32 v30, v44, v30
	v_add_f32_e32 v44, v30, v31
	v_add_f32_e32 v30, 1.0, v88
	v_mul_f32_e32 v31, 0xbfb8aa3b, v44
	v_rcp_f32_e32 v30, v30
	v_exp_f32_e32 v31, v31
	v_cvt_pk_bf16_f32 v43, v28, v43
	v_mov_b32_e32 v50, v109
	v_mul_f32_e32 v45, v45, v30
	v_add_f32_e32 v88, 1.0, v31
	v_pk_mul_f32 v[30:31], v[74:75], v[54:55]
	s_nop 0
	v_add_f32_e32 v28, v8, v30
	v_add_f32_e32 v30, v9, v32
	v_add_f32_e32 v28, v28, v31
	v_add_f32_e32 v54, v30, v33
	v_pk_mul_f32 v[30:31], v[72:73], v[50:51]
	s_nop 0
	v_add_f32_e32 v30, v28, v30
	v_mov_b32_e32 v28, v37
	v_pk_mul_f32 v[32:33], v[16:17], v[28:29]
	v_add_f32_e32 v30, v30, v31
	v_add_f32_e32 v32, v54, v32
	v_add_f32_e32 v31, v32, v33
	v_mul_f32_e32 v32, 0xbfb8aa3b, v30
	v_mul_f32_e32 v33, 0xbfb8aa3b, v31
	v_exp_f32_e32 v32, v32
	v_exp_f32_e32 v33, v33
	v_rcp_f32_e32 v54, v88
	v_or_b32_e32 v88, 6, v90
	v_add_f32_e32 v32, 1.0, v32
	v_add_f32_e32 v33, 1.0, v33
	v_rcp_f32_e32 v32, v32
	v_rcp_f32_e32 v33, v33
	v_mul_f32_e32 v44, v44, v54
	v_cvt_pk_bf16_f32 v44, v45, v44
	v_mul_f32_e32 v30, v30, v32
	v_mul_f32_e32 v31, v31, v33
	v_cvt_pk_bf16_f32 v45, v30, v31
	v_lshl_add_u64 v[30:31], v[116:117], 1, v[70:71]
	global_store_dwordx4 v[30:31], v[42:45], off
	v_add_u32_e32 v30, 9, v63
	v_mad_i64_i32 v[54:55], s[0:1], v30, s14, 0
	v_lshl_add_u64 v[30:31], v[54:55], 1, v[68:69]
	v_cmp_ge_i32_e64 s[0:1], v88, v95
	s_waitcnt vmcnt(7)
	v_mov_b32_e32 v30, v152
	v_mov_b32_e32 v31, v153
	v_mov_b32_e32 v32, v154
	v_mov_b32_e32 v33, v155
	v_lshlrev_b32_e32 v42, 16, v30
	v_and_b32_e32 v43, 0xffff0000, v30
	v_lshlrev_b32_e32 v44, 16, v31
	v_and_b32_e32 v45, 0xffff0000, v31
	v_lshlrev_b32_e32 v30, 16, v32
	v_and_b32_e32 v31, 0xffff0000, v32
	v_lshlrev_b32_e32 v32, 16, v33
	v_and_b32_e32 v33, 0xffff0000, v33
	s_and_saveexec_b64 s[10:11], s[0:1]
	s_cbranch_execz .LBB0_2362
	s_and_saveexec_b64 s[0:1], vcc
	s_xor_b64 s[0:1], exec, s[0:1]
	v_mov_b32_e32 v97, v89
	v_lshl_add_u64 v[100:101], v[92:93], 0, v[96:97]
	s_or_saveexec_b64 s[0:1], s[0:1]
	v_mov_b64_e32 v[96:97], 0x182d0000
	s_xor_b64 exec, exec, s[0:1]
	v_add_u32_e32 v96, 0xfffff809, v90
	v_ashrrev_i32_e32 v97, 31, v96
	v_lshl_add_u64 v[100:101], v[98:99], 0, v[96:97]
	v_mov_b64_e32 v[96:97], 0x10240000
	s_or_b64 exec, exec, s[0:1]
	v_readlane_b32 s16, v252, 12
	v_readlane_b32 s22, v252, 18
	v_readlane_b32 s23, v252, 19
	v_readlane_b32 s17, v252, 13
	v_readlane_b32 s18, v252, 14
	v_lshl_add_u64 v[96:97], s[22:23], 0, v[96:97]
	v_mad_u64_u32 v[96:97], s[0:1], v100, s5, v[96:97]
	v_mov_b32_e32 v88, v97
	v_mad_u64_u32 v[100:101], s[0:1], v101, s5, v[88:89]
	v_mov_b32_e32 v97, v100
	v_lshl_add_u64 v[96:97], v[64:65], 2, v[96:97]
	v_readlane_b32 s19, v252, 15
	v_readlane_b32 s20, v252, 16
	v_readlane_b32 s21, v252, 17
	global_store_dwordx4 v[96:97], v[42:45], off
	global_store_dwordx4 v[96:97], v[30:33], off offset:16
.LBB0_2362:
	s_or_b64 exec, exec, s[10:11]
	v_pk_mul_f32 v[46:47], v[18:19], v[46:47]
	v_pk_mul_f32 v[96:97], v[86:87], v[114:115]
	v_add_f32_e32 v46, v3, v46
	v_add_f32_e32 v88, v2, v96
	v_add_f32_e32 v91, v46, v47
	v_mov_b32_e32 v46, v107
	v_mov_b32_e32 v47, v42
	v_add_f32_e32 v88, v88, v97
	v_pk_mul_f32 v[46:47], v[84:85], v[46:47]
	v_mov_b32_e32 v96, v39
	v_add_f32_e32 v46, v88, v46
	v_add_f32_e32 v88, v46, v47
	v_mul_f32_e32 v46, 0xbfb8aa3b, v88
	v_mov_b32_e32 v97, v43
	v_exp_f32_e32 v100, v46
	v_pk_mul_f32 v[46:47], v[10:11], v[96:97]
	v_pk_mul_f32 v[48:49], v[20:21], v[48:49]
	v_add_f32_e32 v46, v91, v46
	v_add_f32_e32 v91, v46, v47
	v_add_f32_e32 v46, 1.0, v100
	v_mul_f32_e32 v47, 0xbfb8aa3b, v91
	v_rcp_f32_e32 v46, v46
	v_exp_f32_e32 v47, v47
	v_add_f32_e32 v48, v5, v48
	v_add_f32_e32 v100, v48, v49
	v_mul_f32_e32 v88, v88, v46
	v_add_f32_e32 v46, 1.0, v47
	v_rcp_f32_e32 v96, v46
	v_pk_mul_f32 v[46:47], v[82:83], v[112:113]
	v_mov_b32_e32 v48, v41
	v_add_f32_e32 v46, v4, v46
	v_add_f32_e32 v97, v46, v47
	v_mov_b32_e32 v46, v57
	v_mov_b32_e32 v47, v44
	v_pk_mul_f32 v[46:47], v[80:81], v[46:47]
	v_mov_b32_e32 v49, v45
	v_add_f32_e32 v46, v97, v46
	v_add_f32_e32 v97, v46, v47
	v_mul_f32_e32 v46, 0xbfb8aa3b, v97
	v_exp_f32_e32 v101, v46
	v_pk_mul_f32 v[46:47], v[12:13], v[48:49]
	v_pk_mul_f32 v[34:35], v[22:23], v[34:35]
	v_add_f32_e32 v46, v100, v46
	v_add_f32_e32 v47, v46, v47
	v_add_f32_e32 v46, 1.0, v101
	v_rcp_f32_e32 v48, v46
	v_mul_f32_e32 v46, 0xbfb8aa3b, v47
	v_exp_f32_e32 v49, v46
	v_mul_f32_e32 v46, v91, v96
	v_cvt_pk_bf16_f32 v46, v88, v46
	v_mul_f32_e32 v88, v97, v48
	v_add_f32_e32 v48, 1.0, v49
	v_rcp_f32_e32 v91, v48
	v_pk_mul_f32 v[48:49], v[78:79], v[110:111]
	v_add_f32_e32 v34, v7, v34
	v_add_f32_e32 v48, v6, v48
	v_add_f32_e32 v96, v34, v35
	v_mov_b32_e32 v34, v53
	v_mov_b32_e32 v35, v30
	v_add_f32_e32 v48, v48, v49
	v_pk_mul_f32 v[34:35], v[76:77], v[34:35]
	v_mov_b32_e32 v49, v31
	v_add_f32_e32 v34, v48, v34
	v_add_f32_e32 v97, v34, v35
	v_mul_f32_e32 v34, 0xbfb8aa3b, v97
	v_mov_b32_e32 v48, v27
	v_exp_f32_e32 v100, v34
	v_pk_mul_f32 v[34:35], v[14:15], v[48:49]
	v_mul_f32_e32 v47, v47, v91
	v_add_f32_e32 v34, v96, v34
	v_add_f32_e32 v48, v34, v35
	v_add_f32_e32 v34, 1.0, v100
	v_mul_f32_e32 v35, 0xbfb8aa3b, v48
	v_rcp_f32_e32 v34, v34
	v_exp_f32_e32 v35, v35
	v_cvt_pk_bf16_f32 v47, v88, v47
	v_pk_mul_f32 v[36:37], v[24:25], v[36:37]
	v_mul_f32_e32 v49, v97, v34
	v_add_f32_e32 v88, 1.0, v35
	v_pk_mul_f32 v[34:35], v[74:75], v[108:109]
	v_add_f32_e32 v36, v9, v36
	v_add_f32_e32 v34, v8, v34
	v_add_f32_e32 v91, v34, v35
	v_add_f32_e32 v96, v36, v37
	v_mov_b32_e32 v34, v51
	v_mov_b32_e32 v35, v32
	v_mov_b32_e32 v36, v29
	v_mov_b32_e32 v37, v33
	v_pk_mul_f32 v[34:35], v[72:73], v[34:35]
	v_pk_mul_f32 v[36:37], v[16:17], v[36:37]
	v_add_f32_e32 v34, v91, v34
	v_add_f32_e32 v36, v96, v36
	v_add_f32_e32 v34, v34, v35
	v_add_f32_e32 v35, v36, v37
	v_mul_f32_e32 v36, 0xbfb8aa3b, v34
	v_mul_f32_e32 v37, 0xbfb8aa3b, v35
	v_exp_f32_e32 v36, v36
	v_exp_f32_e32 v37, v37
	v_rcp_f32_e32 v88, v88
	v_add_f32_e32 v36, 1.0, v36
	v_add_f32_e32 v37, 1.0, v37
	v_rcp_f32_e32 v36, v36
	v_rcp_f32_e32 v37, v37
	v_mul_f32_e32 v48, v48, v88
	v_cvt_pk_bf16_f32 v48, v49, v48
	v_mul_f32_e32 v34, v34, v36
	v_mul_f32_e32 v35, v35, v37
	v_cvt_pk_bf16_f32 v49, v34, v35
	v_lshl_add_u64 v[34:35], v[54:55], 1, v[70:71]
	global_store_dwordx4 v[34:35], v[46:49], off
	v_add_u32_e32 v34, 10, v63
	v_mad_i64_i32 v[54:55], s[0:1], v34, s14, 0
	v_lshl_add_u64 v[34:35], v[54:55], 1, v[68:69]
	v_or_b32_e32 v88, 7, v90
	v_cmp_ge_i32_e64 s[0:1], v88, v95
	s_waitcnt vmcnt(7)
	v_mov_b32_e32 v34, v156
	v_mov_b32_e32 v35, v157
	v_mov_b32_e32 v36, v158
	v_mov_b32_e32 v37, v159
	v_lshlrev_b32_e32 v46, 16, v34
	v_and_b32_e32 v47, 0xffff0000, v34
	v_lshlrev_b32_e32 v48, 16, v35
	v_and_b32_e32 v49, 0xffff0000, v35
	v_lshlrev_b32_e32 v34, 16, v36
	v_and_b32_e32 v35, 0xffff0000, v36
	v_lshlrev_b32_e32 v36, 16, v37
	v_and_b32_e32 v37, 0xffff0000, v37
	s_and_saveexec_b64 s[10:11], s[0:1]
	s_cbranch_execz .LBB0_2297
	s_and_saveexec_b64 s[0:1], vcc
	s_xor_b64 s[0:1], exec, s[0:1]
	v_mov_b32_e32 v95, v89
	v_lshl_add_u64 v[96:97], v[92:93], 0, v[94:95]
	s_or_saveexec_b64 s[0:1], s[0:1]
	v_mov_b64_e32 v[92:93], 0x182d0000
	s_xor_b64 exec, exec, s[0:1]
	s_cbranch_execz .LBB0_2296
	v_add_u32_e32 v90, 0xfffff80a, v90
	v_ashrrev_i32_e32 v91, 31, v90
	v_lshl_add_u64 v[96:97], v[98:99], 0, v[90:91]
	v_mov_b64_e32 v[92:93], 0x10240000
	s_branch .LBB0_2296
